# adds: P3b split-K small-tile MMA loops issue all operand loads up front (was load-wait-MFMA per k-step, 16 exposed round trips)
# speedup vs baseline: 1.0005x; 1.0005x over previous
.LBB0_767:
	s_and_b32 s43, s12, 0xffffffc0
	v_add_u32_e32 v2, s43, v76
	s_lshl_b32 s43, s20, 11
	v_ashrrev_i32_e32 v3, 31, v2
	s_and_b32 s43, s43, 0x1f0000
	v_lshlrev_b64 v[2:3], 11, v[2:3]
	v_lshl_or_b32 v68, v77, 1, s43
	v_lshl_add_u64 v[72:73], v[70:71], 0, v[2:3]
	v_lshl_add_u64 v[74:75], v[70:71], 0, v[68:69]
	s_movk_i32 s43, 0xffe0
	s_mov_b32 s28, 0x1506e000
	s_mov_b32 s29, 0
	s_mov_b32 s30, 0x1008000
	s_mov_b32 s31, 0
	s_mov_b32 s46, 0x1716e000
	s_mov_b32 s47, 0
	s_mov_b32 s48, 0x1208000
	s_mov_b32 s49, 0
	s_mov_b32 s50, 0x8000
	s_mov_b32 s51, 0
	v_lshl_add_u64 v[124:125], v[72:73], 0, s[2:3]
	v_lshl_add_u64 v[132:133], v[74:75], 0, s[2:3]
	v_lshl_add_u64 v[136:137], v[124:125], 0, s[46:47]
	v_lshl_add_u64 v[144:145], v[132:133], 0, s[48:49]
	v_lshl_add_u64 v[124:125], v[124:125], 0, s[28:29]
	v_lshl_add_u64 v[132:133], v[132:133], 0, s[30:31]
	v_lshl_add_u64 v[126:127], v[124:125], 0, s[50:51]
	v_lshl_add_u64 v[128:129], v[126:127], 0, s[50:51]
	v_lshl_add_u64 v[130:131], v[128:129], 0, s[50:51]
	v_lshl_add_u64 v[138:139], v[136:137], 0, s[50:51]
	v_lshl_add_u64 v[140:141], v[138:139], 0, s[50:51]
	v_lshl_add_u64 v[142:143], v[140:141], 0, s[50:51]
	v_lshl_add_u64 v[134:135], v[132:133], 0, s[50:51]
	v_lshl_add_u64 v[146:147], v[144:145], 0, s[50:51]
	global_load_dwordx4 v[34:37], v[132:133], off
	global_load_dwordx4 v[38:41], v[134:135], off
	global_load_dwordx4 v[42:45], v[124:125], off
	global_load_dwordx4 v[46:49], v[126:127], off
	global_load_dwordx4 v[50:53], v[128:129], off
	global_load_dwordx4 v[54:57], v[130:131], off
	global_load_dwordx4 v[58:61], v[132:133], off offset:64
	global_load_dwordx4 v[62:65], v[134:135], off offset:64
	global_load_dwordx4 v[80:83], v[124:125], off offset:64
	global_load_dwordx4 v[84:87], v[126:127], off offset:64
	global_load_dwordx4 v[88:91], v[128:129], off offset:64
	global_load_dwordx4 v[92:95], v[130:131], off offset:64
	global_load_dwordx4 v[96:99], v[132:133], off offset:128
	global_load_dwordx4 v[100:103], v[134:135], off offset:128
	global_load_dwordx4 v[104:107], v[124:125], off offset:128
	global_load_dwordx4 v[108:111], v[126:127], off offset:128
	global_load_dwordx4 v[112:115], v[128:129], off offset:128
	global_load_dwordx4 v[116:119], v[130:131], off offset:128
	global_load_dwordx4 v[120:123], v[132:133], off offset:192
	global_load_dwordx4 v[186:189], v[134:135], off offset:192
	global_load_dwordx4 v[190:193], v[124:125], off offset:192
	global_load_dwordx4 v[194:197], v[126:127], off offset:192
	global_load_dwordx4 v[198:201], v[128:129], off offset:192
	global_load_dwordx4 v[202:205], v[130:131], off offset:192
	global_load_dwordx4 v[206:209], v[144:145], off
	global_load_dwordx4 v[210:213], v[146:147], off
	global_load_dwordx4 v[214:217], v[136:137], off
	global_load_dwordx4 v[218:221], v[138:139], off
	global_load_dwordx4 v[222:225], v[140:141], off
	global_load_dwordx4 v[226:229], v[142:143], off
	global_load_dwordx4 v[230:233], v[144:145], off offset:64
	global_load_dwordx4 v[234:237], v[146:147], off offset:64
	global_load_dwordx4 v[238:241], v[136:137], off offset:64
	global_load_dwordx4 v[242:245], v[138:139], off offset:64
	global_load_dwordx4 v[246:249], v[140:141], off offset:64
	global_load_dwordx4 v[250:253], v[142:143], off offset:64
	s_waitcnt vmcnt(12)
	v_mfma_f32_16x16x32_bf16 v[30:33], v[34:37], v[42:45], 0
	v_mfma_f32_16x16x32_bf16 v[26:29], v[38:41], v[42:45], 0
	v_mfma_f32_16x16x32_bf16 v[18:21], v[34:37], v[46:49], 0
	v_mfma_f32_16x16x32_bf16 v[14:17], v[38:41], v[46:49], 0
	v_mfma_f32_16x16x32_bf16 v[10:13], v[34:37], v[50:53], 0
	v_mfma_f32_16x16x32_bf16 v[6:9], v[38:41], v[50:53], 0
	v_mfma_f32_16x16x32_bf16 v[2:5], v[34:37], v[54:57], 0
	v_mfma_f32_16x16x32_bf16 v[22:25], v[38:41], v[54:57], 0
	v_mfma_f32_16x16x32_bf16 v[30:33], v[58:61], v[80:83], v[30:33]
	v_mfma_f32_16x16x32_bf16 v[26:29], v[62:65], v[80:83], v[26:29]
	v_mfma_f32_16x16x32_bf16 v[18:21], v[58:61], v[84:87], v[18:21]
	v_mfma_f32_16x16x32_bf16 v[14:17], v[62:65], v[84:87], v[14:17]
	v_mfma_f32_16x16x32_bf16 v[10:13], v[58:61], v[88:91], v[10:13]
	v_mfma_f32_16x16x32_bf16 v[6:9], v[62:65], v[88:91], v[6:9]
	v_mfma_f32_16x16x32_bf16 v[2:5], v[58:61], v[92:95], v[2:5]
	v_mfma_f32_16x16x32_bf16 v[22:25], v[62:65], v[92:95], v[22:25]
	v_mfma_f32_16x16x32_bf16 v[30:33], v[96:99], v[104:107], v[30:33]
	v_mfma_f32_16x16x32_bf16 v[26:29], v[100:103], v[104:107], v[26:29]
	v_mfma_f32_16x16x32_bf16 v[18:21], v[96:99], v[108:111], v[18:21]
	v_mfma_f32_16x16x32_bf16 v[14:17], v[100:103], v[108:111], v[14:17]
	v_mfma_f32_16x16x32_bf16 v[10:13], v[96:99], v[112:115], v[10:13]
	v_mfma_f32_16x16x32_bf16 v[6:9], v[100:103], v[112:115], v[6:9]
	v_mfma_f32_16x16x32_bf16 v[2:5], v[96:99], v[116:119], v[2:5]
	v_mfma_f32_16x16x32_bf16 v[22:25], v[100:103], v[116:119], v[22:25]
	v_mfma_f32_16x16x32_bf16 v[30:33], v[120:123], v[190:193], v[30:33]
	v_mfma_f32_16x16x32_bf16 v[26:29], v[186:189], v[190:193], v[26:29]
	v_mfma_f32_16x16x32_bf16 v[18:21], v[120:123], v[194:197], v[18:21]
	v_mfma_f32_16x16x32_bf16 v[14:17], v[186:189], v[194:197], v[14:17]
	v_mfma_f32_16x16x32_bf16 v[10:13], v[120:123], v[198:201], v[10:13]
	v_mfma_f32_16x16x32_bf16 v[6:9], v[186:189], v[198:201], v[6:9]
	v_mfma_f32_16x16x32_bf16 v[2:5], v[120:123], v[202:205], v[2:5]
	v_mfma_f32_16x16x32_bf16 v[22:25], v[186:189], v[202:205], v[22:25]
	global_load_dwordx4 v[80:83], v[144:145], off offset:128
	global_load_dwordx4 v[84:87], v[146:147], off offset:128
	global_load_dwordx4 v[88:91], v[136:137], off offset:128
	global_load_dwordx4 v[92:95], v[138:139], off offset:128
	global_load_dwordx4 v[96:99], v[140:141], off offset:128
	global_load_dwordx4 v[100:103], v[142:143], off offset:128
	global_load_dwordx4 v[104:107], v[144:145], off offset:192
	global_load_dwordx4 v[108:111], v[146:147], off offset:192
	global_load_dwordx4 v[112:115], v[136:137], off offset:192
	global_load_dwordx4 v[116:119], v[138:139], off offset:192
	global_load_dwordx4 v[120:123], v[140:141], off offset:192
	global_load_dwordx4 v[186:189], v[142:143], off offset:192
	s_nop 7
	s_waitcnt lgkmcnt(0)
	s_barrier
	ds_write_b128 v78, v[30:33]
	ds_write_b128 v78, v[26:29] offset:64
	ds_write_b128 v78, v[18:21] offset:2048
	ds_write_b128 v78, v[14:17] offset:2112
	ds_write_b128 v78, v[10:13] offset:4096
	ds_write_b128 v78, v[6:9] offset:4160
	ds_write_b128 v78, v[2:5] offset:6144
	ds_write_b128 v78, v[22:25] offset:6208
	s_waitcnt lgkmcnt(0)
	s_barrier
	ds_read_b128 v[30:33], v67
	ds_read_b128 v[26:29], v67 offset:8192
	ds_read_b128 v[22:25], v67 offset:16384
	ds_read_b128 v[18:21], v67 offset:24576
	ds_read_b128 v[14:17], v67 offset:32768
	ds_read_b128 v[10:13], v67 offset:40960
	ds_read_b128 v[6:9], v67 offset:49152
	ds_read_b128 v[2:5], v67 offset:57344
	s_waitcnt vmcnt(12)
	v_mfma_f32_16x16x32_bf16 v[62:65], v[206:209], v[214:217], 0
	v_mfma_f32_16x16x32_bf16 v[58:61], v[210:213], v[214:217], 0
	v_mfma_f32_16x16x32_bf16 v[54:57], v[206:209], v[218:221], 0
	v_mfma_f32_16x16x32_bf16 v[46:49], v[210:213], v[218:221], 0
	v_mfma_f32_16x16x32_bf16 v[42:45], v[206:209], v[222:225], 0
	v_mfma_f32_16x16x32_bf16 v[38:41], v[210:213], v[222:225], 0
	v_mfma_f32_16x16x32_bf16 v[34:37], v[206:209], v[226:229], 0
	v_mfma_f32_16x16x32_bf16 v[50:53], v[210:213], v[226:229], 0
	v_mfma_f32_16x16x32_bf16 v[62:65], v[230:233], v[238:241], v[62:65]
	v_mfma_f32_16x16x32_bf16 v[58:61], v[234:237], v[238:241], v[58:61]
	v_mfma_f32_16x16x32_bf16 v[54:57], v[230:233], v[242:245], v[54:57]
	v_mfma_f32_16x16x32_bf16 v[46:49], v[234:237], v[242:245], v[46:49]
	v_mfma_f32_16x16x32_bf16 v[42:45], v[230:233], v[246:249], v[42:45]
	v_mfma_f32_16x16x32_bf16 v[38:41], v[234:237], v[246:249], v[38:41]
	v_mfma_f32_16x16x32_bf16 v[34:37], v[230:233], v[250:253], v[34:37]
	v_mfma_f32_16x16x32_bf16 v[50:53], v[234:237], v[250:253], v[50:53]
	s_waitcnt vmcnt(0)
	v_mfma_f32_16x16x32_bf16 v[62:65], v[80:83], v[88:91], v[62:65]
	v_mfma_f32_16x16x32_bf16 v[58:61], v[84:87], v[88:91], v[58:61]
	v_mfma_f32_16x16x32_bf16 v[54:57], v[80:83], v[92:95], v[54:57]
	v_mfma_f32_16x16x32_bf16 v[46:49], v[84:87], v[92:95], v[46:49]
	v_mfma_f32_16x16x32_bf16 v[42:45], v[80:83], v[96:99], v[42:45]
	v_mfma_f32_16x16x32_bf16 v[38:41], v[84:87], v[96:99], v[38:41]
	v_mfma_f32_16x16x32_bf16 v[34:37], v[80:83], v[100:103], v[34:37]
	v_mfma_f32_16x16x32_bf16 v[50:53], v[84:87], v[100:103], v[50:53]
	v_mfma_f32_16x16x32_bf16 v[62:65], v[104:107], v[112:115], v[62:65]
	v_mfma_f32_16x16x32_bf16 v[58:61], v[108:111], v[112:115], v[58:61]
	v_mfma_f32_16x16x32_bf16 v[54:57], v[104:107], v[116:119], v[54:57]
	v_mfma_f32_16x16x32_bf16 v[46:49], v[108:111], v[116:119], v[46:49]
	v_mfma_f32_16x16x32_bf16 v[42:45], v[104:107], v[120:123], v[42:45]
	v_mfma_f32_16x16x32_bf16 v[38:41], v[108:111], v[120:123], v[38:41]
	v_mfma_f32_16x16x32_bf16 v[34:37], v[104:107], v[186:189], v[34:37]
	v_mfma_f32_16x16x32_bf16 v[50:53], v[108:111], v[186:189], v[50:53]
	s_nop 7
	s_lshl_b32 s43, s42, 1
	s_andn2_b32 s43, s43, 63
	s_addk_i32 s43, 0x4000
	s_waitcnt lgkmcnt(0)
	s_barrier
	ds_write_b128 v78, v[62:65]
	ds_write_b128 v78, v[58:61] offset:64
	ds_write_b128 v78, v[54:57] offset:2048
	ds_write_b128 v78, v[46:49] offset:2112
	ds_write_b128 v78, v[42:45] offset:4096
	ds_write_b128 v78, v[38:41] offset:4160
	ds_write_b128 v78, v[34:37] offset:6144
	ds_write_b128 v78, v[50:53] offset:6208
	v_or_b32_e32 v34, s43, v170
	s_lshl_b32 s44, s42, 5
	v_ashrrev_i32_e32 v35, 31, v34
	s_and_b32 s44, s44, 0x3e0
	v_lshlrev_b64 v[34:35], 10, v[34:35]
	v_or_b32_e32 v34, s44, v34
	v_or_b32_e32 v34, v34, v66
	v_lshlrev_b64 v[62:63], 1, v[34:35]
	v_lshl_add_u64 v[36:37], s[0:1], 0, v[62:63]
	s_waitcnt lgkmcnt(0)
	s_barrier
	v_lshl_add_u64 v[34:35], s[4:5], 0, v[62:63]
	global_load_dwordx2 v[64:65], v[36:37], off
	global_load_dwordx2 v[72:73], v[34:35], off
	v_pk_add_f32 v[74:75], v[32:33], 0 op_sel_hi:[1,0]
	v_pk_add_f32 v[80:81], v[30:31], 0 op_sel_hi:[1,0]
	v_pk_add_f32 v[28:29], v[74:75], v[28:29]
	v_pk_add_f32 v[26:27], v[80:81], v[26:27]
	v_pk_add_f32 v[24:25], v[28:29], v[24:25]
	v_pk_add_f32 v[22:23], v[26:27], v[22:23]
	v_pk_add_f32 v[20:21], v[24:25], v[20:21]
	v_pk_add_f32 v[18:19], v[22:23], v[18:19]
	v_pk_add_f32 v[16:17], v[20:21], v[16:17]
	v_pk_add_f32 v[14:15], v[18:19], v[14:15]
	ds_read_b128 v[30:33], v67
	ds_read_b128 v[34:37], v67 offset:8192
	ds_read_b128 v[38:41], v67 offset:16384
	ds_read_b128 v[42:45], v67 offset:24576
	ds_read_b128 v[46:49], v67 offset:32768
	ds_read_b128 v[50:53], v67 offset:40960
	ds_read_b128 v[54:57], v67 offset:49152
	ds_read_b128 v[58:61], v67 offset:57344
	v_pk_add_f32 v[12:13], v[16:17], v[12:13]
	v_pk_add_f32 v[10:11], v[14:15], v[10:11]
	s_waitcnt lgkmcnt(7)
	v_pk_add_f32 v[14:15], v[32:33], 0 op_sel_hi:[1,0]
	v_pk_add_f32 v[16:17], v[30:31], 0 op_sel_hi:[1,0]
	v_pk_add_f32 v[8:9], v[12:13], v[8:9]
	v_pk_add_f32 v[6:7], v[10:11], v[6:7]
	s_waitcnt lgkmcnt(6)
	v_pk_add_f32 v[10:11], v[14:15], v[36:37]
	v_pk_add_f32 v[12:13], v[16:17], v[34:35]
	v_pk_add_f32 v[4:5], v[8:9], v[4:5]
	v_pk_add_f32 v[2:3], v[6:7], v[2:3]
	s_waitcnt lgkmcnt(5)
	v_pk_add_f32 v[6:7], v[10:11], v[40:41]
	v_pk_add_f32 v[8:9], v[12:13], v[38:39]
	s_waitcnt lgkmcnt(4)
	v_pk_add_f32 v[6:7], v[6:7], v[44:45]
	v_pk_add_f32 v[8:9], v[8:9], v[42:43]
	s_waitcnt lgkmcnt(3)
	v_pk_add_f32 v[6:7], v[6:7], v[48:49]
	v_pk_add_f32 v[8:9], v[8:9], v[46:47]
	s_waitcnt lgkmcnt(2)
	v_pk_add_f32 v[6:7], v[6:7], v[52:53]
	v_pk_add_f32 v[8:9], v[8:9], v[50:51]
	s_waitcnt lgkmcnt(1)
	v_pk_add_f32 v[6:7], v[6:7], v[56:57]
	v_pk_add_f32 v[8:9], v[8:9], v[54:55]
	s_waitcnt lgkmcnt(0)
	v_pk_add_f32 v[6:7], v[6:7], v[60:61]
	v_pk_add_f32 v[8:9], v[8:9], v[58:59]
	v_mov_b32_e32 v10, v2
	v_mov_b32_e32 v2, v4
	v_mov_b32_e32 v11, v8
	v_mov_b32_e32 v8, v3
	v_mov_b32_e32 v3, v6
	v_mov_b32_e32 v6, v5
	s_add_i32 s42, s42, s90
	s_add_i32 s12, s12, s13
	s_add_i32 s20, s20, s21
	v_lshl_add_u64 v[12:13], s[26:27], 0, v[62:63]
	s_cmpk_gt_i32 s42, 0xff
	s_waitcnt vmcnt(1)
	v_lshlrev_b32_e32 v17, 16, v65
	s_waitcnt vmcnt(0)
	v_lshlrev_b32_e32 v16, 16, v73
	v_lshlrev_b32_e32 v5, 16, v64
	v_lshlrev_b32_e32 v4, 16, v72
	v_and_b32_e32 v15, 0xffff0000, v64
	v_and_b32_e32 v14, 0xffff0000, v72
	v_and_b32_e32 v19, 0xffff0000, v65
	v_and_b32_e32 v18, 0xffff0000, v73
	v_pk_mul_f32 v[2:3], v[2:3], v[16:17]
	v_pk_mul_f32 v[4:5], v[10:11], v[4:5]
	v_pk_mul_f32 v[8:9], v[8:9], v[14:15]
	v_pk_mul_f32 v[6:7], v[6:7], v[18:19]
	v_add_f32_e32 v3, v2, v3
	v_add_f32_e32 v4, v4, v5
	v_add_f32_e32 v5, v8, v9
	v_add_f32_e32 v6, v6, v7
	v_cvt_pk_bf16_f32 v2, v4, v5
	v_cvt_pk_bf16_f32 v3, v3, v6
	global_store_dwordx2 v[12:13], v[2:3], off
	s_cbranch_scc0 .LBB0_767
